# in-projection GEMM epilogue: the bf16 output stores drop the non-temporal hint so the mixers' inputs can stay in cache
# speedup vs baseline: 1.0005x; 1.0005x over previous
; DI unsigned pack2(float a, float b) { f32v2 v = {a, b}; bf16v2 r = __builtin_convertvector(v, bf16v2); return __builtin_bit_cast(unsigned, r); }
;     ...
; #pragma unroll
;       for (int mi = 0; mi < 2; ++mi)
; #pragma unroll
;         for (int ni = 0; ni < 2; ++ni) {
;           const int col = n0e + cb + ni * 32;
;           if (col < INW && (dummy < 2 || acc[mi][ni][0] == 12345.678f)) {
;             const bool odd = (cb & 1) != 0;
; #pragma unroll
;             for (int i = 0; i < 16; i += 2) {
;               const float a = acc[mi][ni][i], b2 = acc[mi][ni][i + 1];
;               const float recv = dpp_f(odd ? a : b2, 0);
;               const int row = m0e + rb + mi * 32 + (i & 3) + 8 * (i >> 2) + (odd ? 1 : 0);
;               const unsigned w = odd ? pack2(recv, b2) : pack2(a, recv);
;               __builtin_nontemporal_store(w, (unsigned*)(P.pbuf + (size_t)row * INW + (col & ~1)));
;             }
;           }
.LBB0_580:
	s_andn2_saveexec_b64 s[0:1], s[0:1]
	v_lshrrev_b32_e32 v64, 6, v68
	s_or_b64 exec, exec, s[0:1]
	v_cmp_gt_i32_e32 vcc, 0, v64
	s_and_saveexec_b64 s[0:1], vcc
	s_xor_b64 s[2:3], exec, s[0:1]
	s_cbranch_execz .LBB0_592
	v_add_u32_e32 v74, s4, v66
	v_and_b32_e32 v64, 1, v66
	v_cmp_eq_u32_e32 vcc, 0, v64
	v_add3_u32 v66, v65, s9, v64
	s_movk_i32 s0, 0xcc0
	v_and_b32_e32 v64, -2, v74
	v_cmp_gt_i32_e64 s[0:1], s0, v74
	v_add_u32_e32 v73, 2, v66
	v_add_u32_e32 v72, 8, v66
	v_add_u32_e32 v71, 10, v66
	v_add_u32_e32 v70, 16, v66
	v_add_u32_e32 v69, 18, v66
	v_add_u32_e32 v68, 24, v66
	v_add_u32_e32 v67, 26, v66
	v_ashrrev_i32_e32 v65, 31, v64
	s_and_saveexec_b64 s[4:5], s[0:1]
	s_cbranch_execz .LBB0_585
	v_cndmask_b32_e32 v75, v48, v49, vcc
	v_lshl_add_u64 v[76:77], v[64:65], 1, s[64:65]
	s_movk_i32 s10, 0x1980
	v_mov_b32_dpp v75, v75 quad_perm:[1,0,3,2] row_mask:0xf bank_mask:0xf bound_ctrl:1
	v_cndmask_b32_e32 v49, v49, v75, vcc
	v_cndmask_b32_e32 v48, v75, v48, vcc
	v_cvt_pk_bf16_f32 v75, v48, v49
	v_mad_i64_i32 v[48:49], s[6:7], v66, s10, v[76:77]
	global_store_dword v[48:49], v75, off
	v_cndmask_b32_e32 v48, v50, v51, vcc
	s_nop 1
	v_mov_b32_dpp v48, v48 quad_perm:[1,0,3,2] row_mask:0xf bank_mask:0xf bound_ctrl:1
	v_cndmask_b32_e32 v49, v51, v48, vcc
	v_cndmask_b32_e32 v48, v48, v50, vcc
	v_cvt_pk_bf16_f32 v50, v48, v49
	v_mad_i64_i32 v[48:49], s[6:7], v73, s10, v[76:77]
	global_store_dword v[48:49], v50, off
	v_cndmask_b32_e32 v48, v52, v53, vcc
	s_nop 1
	v_mov_b32_dpp v48, v48 quad_perm:[1,0,3,2] row_mask:0xf bank_mask:0xf bound_ctrl:1
	v_cndmask_b32_e32 v49, v53, v48, vcc
	v_cndmask_b32_e32 v48, v48, v52, vcc
	v_cvt_pk_bf16_f32 v50, v48, v49
	v_mad_i64_i32 v[48:49], s[6:7], v72, s10, v[76:77]
	global_store_dword v[48:49], v50, off
	v_cndmask_b32_e32 v48, v54, v55, vcc
	s_nop 1
	v_mov_b32_dpp v48, v48 quad_perm:[1,0,3,2] row_mask:0xf bank_mask:0xf bound_ctrl:1
	v_cndmask_b32_e32 v49, v55, v48, vcc
	v_cndmask_b32_e32 v48, v48, v54, vcc
	v_cvt_pk_bf16_f32 v50, v48, v49
	v_mad_i64_i32 v[48:49], s[6:7], v71, s10, v[76:77]
	global_store_dword v[48:49], v50, off
	v_cndmask_b32_e32 v48, v56, v57, vcc
	s_nop 1
	v_mov_b32_dpp v48, v48 quad_perm:[1,0,3,2] row_mask:0xf bank_mask:0xf bound_ctrl:1
	v_cndmask_b32_e32 v49, v57, v48, vcc
	v_cndmask_b32_e32 v48, v48, v56, vcc
	v_cvt_pk_bf16_f32 v50, v48, v49
	v_mad_i64_i32 v[48:49], s[6:7], v70, s10, v[76:77]
	global_store_dword v[48:49], v50, off
	v_cndmask_b32_e32 v48, v58, v59, vcc
	s_nop 1
	v_mov_b32_dpp v48, v48 quad_perm:[1,0,3,2] row_mask:0xf bank_mask:0xf bound_ctrl:1
	v_cndmask_b32_e32 v49, v59, v48, vcc
	v_cndmask_b32_e32 v48, v48, v58, vcc
	v_cvt_pk_bf16_f32 v50, v48, v49
	v_mad_i64_i32 v[48:49], s[6:7], v69, s10, v[76:77]
	global_store_dword v[48:49], v50, off
	v_cndmask_b32_e32 v48, v60, v61, vcc
	s_nop 1
	v_mov_b32_dpp v48, v48 quad_perm:[1,0,3,2] row_mask:0xf bank_mask:0xf bound_ctrl:1
	v_cndmask_b32_e32 v49, v61, v48, vcc
	v_cndmask_b32_e32 v48, v48, v60, vcc
	v_cvt_pk_bf16_f32 v50, v48, v49
	v_mad_i64_i32 v[48:49], s[6:7], v68, s10, v[76:77]
	global_store_dword v[48:49], v50, off
	v_cndmask_b32_e32 v48, v62, v63, vcc
	s_nop 1
	v_mov_b32_dpp v48, v48 quad_perm:[1,0,3,2] row_mask:0xf bank_mask:0xf bound_ctrl:1
	v_cndmask_b32_e32 v49, v63, v48, vcc
	v_cndmask_b32_e32 v48, v48, v62, vcc
	v_cvt_pk_bf16_f32 v50, v48, v49
	v_mad_i64_i32 v[48:49], s[6:7], v67, s10, v[76:77]
	global_store_dword v[48:49], v50, off
.LBB0_585:
	s_or_b64 exec, exec, s[4:5]
	v_add_u32_e32 v48, 32, v74
	s_movk_i32 s4, 0xca0
	v_and_b32_e32 v48, -2, v48
	v_cmp_gt_i32_e64 s[4:5], s4, v74
	v_ashrrev_i32_e32 v49, 31, v48
	s_and_saveexec_b64 s[6:7], s[4:5]
	s_cbranch_execz .LBB0_587
	v_cndmask_b32_e32 v52, v32, v33, vcc
	v_lshl_add_u64 v[50:51], v[48:49], 1, s[64:65]
	s_movk_i32 s12, 0x1980
	v_mov_b32_dpp v52, v52 quad_perm:[1,0,3,2] row_mask:0xf bank_mask:0xf bound_ctrl:1
	v_cndmask_b32_e32 v33, v33, v52, vcc
	v_cndmask_b32_e32 v32, v52, v32, vcc
	v_cvt_pk_bf16_f32 v52, v32, v33
	v_mad_i64_i32 v[32:33], s[10:11], v66, s12, v[50:51]
	global_store_dword v[32:33], v52, off
	v_cndmask_b32_e32 v32, v34, v35, vcc
	s_nop 1
	v_mov_b32_dpp v32, v32 quad_perm:[1,0,3,2] row_mask:0xf bank_mask:0xf bound_ctrl:1
	v_cndmask_b32_e32 v33, v35, v32, vcc
	v_cndmask_b32_e32 v32, v32, v34, vcc
	v_cvt_pk_bf16_f32 v34, v32, v33
	v_mad_i64_i32 v[32:33], s[10:11], v73, s12, v[50:51]
	global_store_dword v[32:33], v34, off
	v_cndmask_b32_e32 v32, v36, v37, vcc
	s_nop 1
	v_mov_b32_dpp v32, v32 quad_perm:[1,0,3,2] row_mask:0xf bank_mask:0xf bound_ctrl:1
	v_cndmask_b32_e32 v33, v37, v32, vcc
	v_cndmask_b32_e32 v32, v32, v36, vcc
	v_cvt_pk_bf16_f32 v34, v32, v33
	v_mad_i64_i32 v[32:33], s[10:11], v72, s12, v[50:51]
	global_store_dword v[32:33], v34, off
	v_cndmask_b32_e32 v32, v38, v39, vcc
	s_nop 1
	v_mov_b32_dpp v32, v32 quad_perm:[1,0,3,2] row_mask:0xf bank_mask:0xf bound_ctrl:1
	v_cndmask_b32_e32 v33, v39, v32, vcc
	v_cndmask_b32_e32 v32, v32, v38, vcc
	v_cvt_pk_bf16_f32 v34, v32, v33
	v_mad_i64_i32 v[32:33], s[10:11], v71, s12, v[50:51]
	global_store_dword v[32:33], v34, off
	v_cndmask_b32_e32 v32, v40, v41, vcc
	s_nop 1
	v_mov_b32_dpp v32, v32 quad_perm:[1,0,3,2] row_mask:0xf bank_mask:0xf bound_ctrl:1
	v_cndmask_b32_e32 v33, v41, v32, vcc
	v_cndmask_b32_e32 v32, v32, v40, vcc
	v_cvt_pk_bf16_f32 v34, v32, v33
	v_mad_i64_i32 v[32:33], s[10:11], v70, s12, v[50:51]
	global_store_dword v[32:33], v34, off
	v_cndmask_b32_e32 v32, v42, v43, vcc
	s_nop 1
	v_mov_b32_dpp v32, v32 quad_perm:[1,0,3,2] row_mask:0xf bank_mask:0xf bound_ctrl:1
	v_cndmask_b32_e32 v33, v43, v32, vcc
	v_cndmask_b32_e32 v32, v32, v42, vcc
	v_cvt_pk_bf16_f32 v34, v32, v33
	v_mad_i64_i32 v[32:33], s[10:11], v69, s12, v[50:51]
	global_store_dword v[32:33], v34, off
	v_cndmask_b32_e32 v32, v44, v45, vcc
	s_nop 1
	v_mov_b32_dpp v32, v32 quad_perm:[1,0,3,2] row_mask:0xf bank_mask:0xf bound_ctrl:1
	v_cndmask_b32_e32 v33, v45, v32, vcc
	v_cndmask_b32_e32 v32, v32, v44, vcc
	v_cvt_pk_bf16_f32 v34, v32, v33
	v_mad_i64_i32 v[32:33], s[10:11], v68, s12, v[50:51]
	global_store_dword v[32:33], v34, off
	v_cndmask_b32_e32 v32, v46, v47, vcc
	s_nop 1
	v_mov_b32_dpp v32, v32 quad_perm:[1,0,3,2] row_mask:0xf bank_mask:0xf bound_ctrl:1
	v_cndmask_b32_e32 v33, v47, v32, vcc
	v_cndmask_b32_e32 v32, v32, v46, vcc
	v_cvt_pk_bf16_f32 v34, v32, v33
	v_mad_i64_i32 v[32:33], s[10:11], v67, s12, v[50:51]
	global_store_dword v[32:33], v34, off
; DI unsigned pack2(float a, float b) { f32v2 v = {a, b}; bf16v2 r = __builtin_convertvector(v, bf16v2); return __builtin_bit_cast(unsigned, r); }
;     ...
; #pragma unroll
;       for (int mi = 0; mi < 2; ++mi)
; #pragma unroll
;         for (int ni = 0; ni < 2; ++ni) {
;           const int col = n0e + cb + ni * 32;
;           if (col < INW && (dummy < 2 || acc[mi][ni][0] == 12345.678f)) {
;             const bool odd = (cb & 1) != 0;
; #pragma unroll
;             for (int i = 0; i < 16; i += 2) {
;               const float a = acc[mi][ni][i], b2 = acc[mi][ni][i + 1];
;               const float recv = dpp_f(odd ? a : b2, 0);
;               const int row = m0e + rb + mi * 32 + (i & 3) + 8 * (i >> 2) + (odd ? 1 : 0);
;               const unsigned w = odd ? pack2(recv, b2) : pack2(a, recv);
;               __builtin_nontemporal_store(w, (unsigned*)(P.pbuf + (size_t)row * INW + (col & ~1)));
;             }
;           }
.LBB0_587:
	s_or_b64 exec, exec, s[6:7]
	v_add_u32_e32 v39, 32, v66
	v_add_u32_e32 v38, 34, v66
	v_add_u32_e32 v37, 40, v66
	v_add_u32_e32 v36, 42, v66
	v_add_u32_e32 v35, 48, v66
	v_add_u32_e32 v34, 50, v66
	v_add_u32_e32 v33, 56, v66
	v_add_u32_e32 v32, 58, v66
	s_and_saveexec_b64 s[6:7], s[0:1]
	s_cbranch_execz .LBB0_589
	v_cndmask_b32_e32 v42, v16, v17, vcc
	v_lshl_add_u64 v[40:41], v[64:65], 1, s[64:65]
	s_movk_i32 s10, 0x1980
	v_mov_b32_dpp v42, v42 quad_perm:[1,0,3,2] row_mask:0xf bank_mask:0xf bound_ctrl:1
	v_cndmask_b32_e32 v17, v17, v42, vcc
	v_cndmask_b32_e32 v16, v42, v16, vcc
	v_cvt_pk_bf16_f32 v42, v16, v17
	v_mad_i64_i32 v[16:17], s[0:1], v39, s10, v[40:41]
	global_store_dword v[16:17], v42, off
	v_cndmask_b32_e32 v16, v18, v19, vcc
	s_nop 1
	v_mov_b32_dpp v16, v16 quad_perm:[1,0,3,2] row_mask:0xf bank_mask:0xf bound_ctrl:1
	v_cndmask_b32_e32 v17, v19, v16, vcc
	v_cndmask_b32_e32 v16, v16, v18, vcc
	v_cvt_pk_bf16_f32 v18, v16, v17
	v_mad_i64_i32 v[16:17], s[0:1], v38, s10, v[40:41]
	global_store_dword v[16:17], v18, off
	v_cndmask_b32_e32 v16, v20, v21, vcc
	s_nop 1
	v_mov_b32_dpp v16, v16 quad_perm:[1,0,3,2] row_mask:0xf bank_mask:0xf bound_ctrl:1
	v_cndmask_b32_e32 v17, v21, v16, vcc
	v_cndmask_b32_e32 v16, v16, v20, vcc
	v_cvt_pk_bf16_f32 v18, v16, v17
	v_mad_i64_i32 v[16:17], s[0:1], v37, s10, v[40:41]
	global_store_dword v[16:17], v18, off
	v_cndmask_b32_e32 v16, v22, v23, vcc
	s_nop 1
	v_mov_b32_dpp v16, v16 quad_perm:[1,0,3,2] row_mask:0xf bank_mask:0xf bound_ctrl:1
	v_cndmask_b32_e32 v17, v23, v16, vcc
	v_cndmask_b32_e32 v16, v16, v22, vcc
	v_cvt_pk_bf16_f32 v18, v16, v17
	v_mad_i64_i32 v[16:17], s[0:1], v36, s10, v[40:41]
	global_store_dword v[16:17], v18, off
	v_cndmask_b32_e32 v16, v24, v25, vcc
	s_nop 1
	v_mov_b32_dpp v16, v16 quad_perm:[1,0,3,2] row_mask:0xf bank_mask:0xf bound_ctrl:1
	v_cndmask_b32_e32 v17, v25, v16, vcc
	v_cndmask_b32_e32 v16, v16, v24, vcc
	v_cvt_pk_bf16_f32 v18, v16, v17
	v_mad_i64_i32 v[16:17], s[0:1], v35, s10, v[40:41]
	global_store_dword v[16:17], v18, off
	v_cndmask_b32_e32 v16, v26, v27, vcc
	s_nop 1
	v_mov_b32_dpp v16, v16 quad_perm:[1,0,3,2] row_mask:0xf bank_mask:0xf bound_ctrl:1
	v_cndmask_b32_e32 v17, v27, v16, vcc
	v_cndmask_b32_e32 v16, v16, v26, vcc
	v_cvt_pk_bf16_f32 v18, v16, v17
	v_mad_i64_i32 v[16:17], s[0:1], v34, s10, v[40:41]
	global_store_dword v[16:17], v18, off
	v_cndmask_b32_e32 v16, v28, v29, vcc
	s_nop 1
	v_mov_b32_dpp v16, v16 quad_perm:[1,0,3,2] row_mask:0xf bank_mask:0xf bound_ctrl:1
	v_cndmask_b32_e32 v17, v29, v16, vcc
	v_cndmask_b32_e32 v16, v16, v28, vcc
	v_cvt_pk_bf16_f32 v18, v16, v17
	v_mad_i64_i32 v[16:17], s[0:1], v33, s10, v[40:41]
	global_store_dword v[16:17], v18, off
	v_cndmask_b32_e32 v16, v30, v31, vcc
	s_nop 1
	v_mov_b32_dpp v16, v16 quad_perm:[1,0,3,2] row_mask:0xf bank_mask:0xf bound_ctrl:1
	v_cndmask_b32_e32 v17, v31, v16, vcc
	v_cndmask_b32_e32 v16, v16, v30, vcc
	v_cvt_pk_bf16_f32 v18, v16, v17
	v_mad_i64_i32 v[16:17], s[0:1], v32, s10, v[40:41]
	global_store_dword v[16:17], v18, off
.LBB0_589:
	s_or_b64 exec, exec, s[6:7]
	s_and_saveexec_b64 s[0:1], s[4:5]
	s_cbranch_execz .LBB0_591
	v_cndmask_b32_e32 v18, v0, v1, vcc
	v_lshl_add_u64 v[16:17], v[48:49], 1, s[64:65]
	s_movk_i32 s6, 0x1980
	v_mov_b32_dpp v18, v18 quad_perm:[1,0,3,2] row_mask:0xf bank_mask:0xf bound_ctrl:1
	v_cndmask_b32_e32 v1, v1, v18, vcc
	v_cndmask_b32_e32 v0, v18, v0, vcc
	v_cvt_pk_bf16_f32 v18, v0, v1
	v_mad_i64_i32 v[0:1], s[4:5], v39, s6, v[16:17]
	global_store_dword v[0:1], v18, off
	v_cndmask_b32_e32 v0, v2, v3, vcc
	s_nop 1
	v_mov_b32_dpp v0, v0 quad_perm:[1,0,3,2] row_mask:0xf bank_mask:0xf bound_ctrl:1
	v_cndmask_b32_e32 v1, v3, v0, vcc
	v_cndmask_b32_e32 v0, v0, v2, vcc
	v_cvt_pk_bf16_f32 v2, v0, v1
	v_mad_i64_i32 v[0:1], s[4:5], v38, s6, v[16:17]
	global_store_dword v[0:1], v2, off
	v_cndmask_b32_e32 v0, v4, v5, vcc
	s_nop 1
	v_mov_b32_dpp v0, v0 quad_perm:[1,0,3,2] row_mask:0xf bank_mask:0xf bound_ctrl:1
	v_cndmask_b32_e32 v1, v5, v0, vcc
	v_cndmask_b32_e32 v0, v0, v4, vcc
	v_cvt_pk_bf16_f32 v2, v0, v1
	v_mad_i64_i32 v[0:1], s[4:5], v37, s6, v[16:17]
	global_store_dword v[0:1], v2, off
	v_cndmask_b32_e32 v0, v6, v7, vcc
	s_nop 1
	v_mov_b32_dpp v0, v0 quad_perm:[1,0,3,2] row_mask:0xf bank_mask:0xf bound_ctrl:1
	v_cndmask_b32_e32 v1, v7, v0, vcc
	v_cndmask_b32_e32 v0, v0, v6, vcc
	v_cvt_pk_bf16_f32 v2, v0, v1
	v_mad_i64_i32 v[0:1], s[4:5], v36, s6, v[16:17]
	global_store_dword v[0:1], v2, off
	v_cndmask_b32_e32 v0, v8, v9, vcc
	s_nop 1
	v_mov_b32_dpp v0, v0 quad_perm:[1,0,3,2] row_mask:0xf bank_mask:0xf bound_ctrl:1
	v_cndmask_b32_e32 v1, v9, v0, vcc
	v_cndmask_b32_e32 v0, v0, v8, vcc
	v_cvt_pk_bf16_f32 v2, v0, v1
	v_mad_i64_i32 v[0:1], s[4:5], v35, s6, v[16:17]
	global_store_dword v[0:1], v2, off
	v_cndmask_b32_e32 v0, v10, v11, vcc
	s_nop 1
	v_mov_b32_dpp v0, v0 quad_perm:[1,0,3,2] row_mask:0xf bank_mask:0xf bound_ctrl:1
	v_cndmask_b32_e32 v1, v11, v0, vcc
	v_cndmask_b32_e32 v0, v0, v10, vcc
	v_cvt_pk_bf16_f32 v2, v0, v1
	v_mad_i64_i32 v[0:1], s[4:5], v34, s6, v[16:17]
	global_store_dword v[0:1], v2, off
	v_cndmask_b32_e32 v0, v12, v13, vcc
	s_nop 1
	v_mov_b32_dpp v0, v0 quad_perm:[1,0,3,2] row_mask:0xf bank_mask:0xf bound_ctrl:1
	v_cndmask_b32_e32 v1, v13, v0, vcc
	v_cndmask_b32_e32 v0, v0, v12, vcc
	v_cvt_pk_bf16_f32 v2, v0, v1
	v_mad_i64_i32 v[0:1], s[4:5], v33, s6, v[16:17]
	global_store_dword v[0:1], v2, off
	v_cndmask_b32_e32 v0, v14, v15, vcc
	s_nop 1
	v_mov_b32_dpp v0, v0 quad_perm:[1,0,3,2] row_mask:0xf bank_mask:0xf bound_ctrl:1
	v_cndmask_b32_e32 v1, v15, v0, vcc
	v_cndmask_b32_e32 v0, v0, v14, vcc
	v_cvt_pk_bf16_f32 v2, v0, v1
	v_mad_i64_i32 v[0:1], s[4:5], v32, s6, v[16:17]
	global_store_dword v[0:1], v2, off
